# combined: P5/P6 epilogue load batching (+P6 full-line y access via DPP) and relaxed first-iteration K-loop waits
# speedup vs baseline: 1.0202x; 1.0019x over previous
; #define PG8_STAGE(bufoff, gbase, voff) do { _Pragma("unroll") for (int _i = 0; _i < 2; ++_i) \
;         __builtin_amdgcn_global_load_lds((const unsigned*)((const char*)(gbase) + (voff)[_i]), (PG8_LAS unsigned*)(lds + (bufoff) + ldsw + _i * 8192), 16, 0, 0); } while (0)
; #define PG8_LDA(dst, b, h) do { _Pragma("unroll") for (int m = 0; m < 4; ++m) _Pragma("unroll") for (int k = 0; k < 2; ++k) dst[m][k] = *(const PG8_LAS bf16x8*)(lds + PG8_SA(b, h) + aoff + m * 2048 + k * 1024); } while (0)
; #define PG8_LDB(dst, b, h) do { _Pragma("unroll") for (int n = 0; n < 2; ++n) _Pragma("unroll") for (int k = 0; k < 2; ++k) dst[n][k] = *(const PG8_LAS bf16x8*)(lds + PG8_SB(b, h) + boff + n * 2048 + k * 1024); } while (0)
; #define PG8_MMA(ai, bj, At, Bt) do { __builtin_amdgcn_s_setprio(1); _Pragma("unroll") for (int m = 0; m < 4; ++m) _Pragma("unroll") for (int n = 0; n < 2; ++n) _Pragma("unroll") for (int k = 0; k < 2; ++k) \
;         acc[ai][bj][m][n] = __builtin_amdgcn_mfma_f32_16x16x32_bf16(Bt[n][k], At[m][k], acc[ai][bj][m][n], 0, 0, 0); __builtin_amdgcn_s_setprio(0); } while (0)
; #define PG8_WAIT_V(n) asm volatile("s_waitcnt vmcnt(" #n ")" ::: "memory")
; #define PG8_WAIT_L(n) asm volatile("s_waitcnt lgkmcnt(" #n ")" ::: "memory")
; #define PG8_BAR __builtin_amdgcn_s_barrier()
; #define PG8_SCHED __builtin_amdgcn_sched_barrier(0)
; template <class Epi, class Sched, bool ALIGN_EPI = false, bool SP2 = false>
; __device__ __forceinline__ void gemm_phase(PG8_LAS unsigned char* lds, const Gemm g, const Sched& S, const Epi& E) {
;     ...
;             PG8_WAIT_V(8); PG8_WAIT_L(0); PG8_BAR; PG8_MMA(0, 0, At, B0); PG8_MMA(0, 1, At, B1); PG8_BAR; PG8_SCHED;
;             PG8_LDA(At, 0, 1); PG8_STAGE(PG8_SB(0, 0), b2, voffB); PG8_STAGE(PG8_SB(0, 1), b2 + hstep, voffB); PG8_STAGE(PG8_SA(0, 0), a2, voffA);
;             PG8_WAIT_V(8); PG8_WAIT_L(0); PG8_BAR; PG8_MMA(1, 0, At, B0); PG8_MMA(1, 1, At, B1); PG8_BAR; PG8_SCHED;
;             PG8_LDB(B0, 1, 0); PG8_LDB(B1, 1, 1); PG8_SCHED; PG8_LDA(At, 1, 0); PG8_STAGE(PG8_SA(0, 1), a2 + hstep, voffA);
;             PG8_WAIT_V(8); PG8_WAIT_L(0); PG8_BAR; PG8_MMA(0, 0, At, B0); PG8_MMA(0, 1, At, B1); PG8_BAR; PG8_SCHED;
.Lrj_P5_1:
	s_waitcnt lgkmcnt(0)
	s_barrier
	s_setprio 1
	s_waitcnt lgkmcnt(0)
	v_mfma_f32_16x16x32_bf16 v[60:63], v[144:147], v[184:187], v[60:63]
	v_mfma_f32_16x16x32_bf16 v[56:59], v[160:163], v[184:187], v[56:59]
	v_mfma_f32_16x16x32_bf16 v[44:47], v[144:147], v[192:195], v[44:47]
	v_mfma_f32_16x16x32_bf16 v[40:43], v[160:163], v[192:195], v[40:43]
	v_mfma_f32_16x16x32_bf16 v[28:31], v[144:147], v[200:203], v[28:31]
	v_mfma_f32_16x16x32_bf16 v[24:27], v[160:163], v[200:203], v[24:27]
	v_mfma_f32_16x16x32_bf16 v[12:15], v[144:147], v[208:211], v[12:15]
	v_mfma_f32_16x16x32_bf16 v[8:11], v[160:163], v[208:211], v[8:11]
	v_mfma_f32_16x16x32_bf16 v[60:63], v[156:159], v[188:191], v[60:63]
	v_mfma_f32_16x16x32_bf16 v[56:59], v[164:167], v[188:191], v[56:59]
	v_mfma_f32_16x16x32_bf16 v[44:47], v[156:159], v[196:199], v[44:47]
	v_mfma_f32_16x16x32_bf16 v[40:43], v[164:167], v[196:199], v[40:43]
	v_mfma_f32_16x16x32_bf16 v[28:31], v[156:159], v[204:207], v[28:31]
	v_mfma_f32_16x16x32_bf16 v[24:27], v[164:167], v[204:207], v[24:27]
	v_mfma_f32_16x16x32_bf16 v[12:15], v[156:159], v[212:215], v[12:15]
	v_mfma_f32_16x16x32_bf16 v[8:11], v[164:167], v[212:215], v[8:11]
	s_setprio 0
	s_setprio 1
	v_mfma_f32_16x16x32_bf16 v[52:55], v[168:171], v[184:187], v[52:55]
	v_mfma_f32_16x16x32_bf16 v[48:51], v[176:179], v[184:187], v[48:51]
	v_mfma_f32_16x16x32_bf16 v[36:39], v[168:171], v[192:195], v[36:39]
	v_mfma_f32_16x16x32_bf16 v[32:35], v[176:179], v[192:195], v[32:35]
	v_mfma_f32_16x16x32_bf16 v[20:23], v[168:171], v[200:203], v[20:23]
	v_mfma_f32_16x16x32_bf16 v[16:19], v[176:179], v[200:203], v[16:19]
	v_mfma_f32_16x16x32_bf16 v[4:7], v[168:171], v[208:211], v[4:7]
	v_mfma_f32_16x16x32_bf16 v[0:3], v[176:179], v[208:211], v[0:3]
	v_mfma_f32_16x16x32_bf16 v[52:55], v[172:175], v[188:191], v[52:55]
	v_mfma_f32_16x16x32_bf16 v[48:51], v[180:183], v[188:191], v[48:51]
	v_mfma_f32_16x16x32_bf16 v[36:39], v[172:175], v[196:199], v[36:39]
	v_mfma_f32_16x16x32_bf16 v[32:35], v[180:183], v[196:199], v[32:35]
	v_mfma_f32_16x16x32_bf16 v[20:23], v[172:175], v[204:207], v[20:23]
	v_mfma_f32_16x16x32_bf16 v[16:19], v[180:183], v[204:207], v[16:19]
	v_mfma_f32_16x16x32_bf16 v[4:7], v[172:175], v[212:215], v[4:7]
	v_mfma_f32_16x16x32_bf16 v[0:3], v[180:183], v[212:215], v[0:3]
	s_setprio 0
	s_barrier
	s_add_i32 s66, 0, 0x18000
	v_add_u32_e32 v155, s66, v149
	s_add_i32 s67, 0, 0x1c000
	ds_read_b128 v[144:147], v155
	ds_read_b128 v[156:159], v155 offset:1024
	ds_read_b128 v[160:163], v155 offset:2048
	ds_read_b128 v[164:167], v155 offset:3072
	v_add_u32_e32 v155, s67, v149
	ds_read_b128 v[168:171], v155
	ds_read_b128 v[172:175], v155 offset:1024
	ds_read_b128 v[176:179], v155 offset:2048
	ds_read_b128 v[180:183], v155 offset:3072
	s_add_u32 s36, s36, 0x40000
	s_addc_u32 s37, s37, 0
	s_mov_b32 m0, s43
	v_lshl_add_u64 v[224:225], s[36:37], 0, v[134:135]
	ds_read_b128 v[184:187], v153 offset:32768
	ds_read_b128 v[188:191], v153 offset:33792
	ds_read_b128 v[192:195], v153 offset:34816
	ds_read_b128 v[196:199], v153 offset:35840
	ds_read_b128 v[200:203], v153 offset:36864
	ds_read_b128 v[204:207], v153 offset:37888
	ds_read_b128 v[208:211], v153 offset:38912
	ds_read_b128 v[212:215], v153 offset:39936
	global_load_lds_dwordx4 v[224:225], off
	v_lshl_add_u64 v[224:225], s[36:37], 0, v[130:131]
	s_mov_b32 m0, s46
	s_nop 0
	global_load_lds_dwordx4 v[224:225], off
	s_waitcnt vmcnt(8)
	s_waitcnt lgkmcnt(0)
	s_barrier
	s_setprio 1
	s_waitcnt lgkmcnt(0)
	v_mfma_f32_16x16x32_bf16 v[124:127], v[144:147], v[184:187], v[124:127]
	v_mfma_f32_16x16x32_bf16 v[120:123], v[160:163], v[184:187], v[120:123]
	v_mfma_f32_16x16x32_bf16 v[108:111], v[144:147], v[192:195], v[108:111]
	v_mfma_f32_16x16x32_bf16 v[104:107], v[160:163], v[192:195], v[104:107]
	v_mfma_f32_16x16x32_bf16 v[92:95], v[144:147], v[200:203], v[92:95]
	v_mfma_f32_16x16x32_bf16 v[88:91], v[160:163], v[200:203], v[88:91]
	v_mfma_f32_16x16x32_bf16 v[76:79], v[144:147], v[208:211], v[76:79]
	v_mfma_f32_16x16x32_bf16 v[72:75], v[160:163], v[208:211], v[72:75]
	v_mfma_f32_16x16x32_bf16 v[124:127], v[156:159], v[188:191], v[124:127]
	v_mfma_f32_16x16x32_bf16 v[120:123], v[164:167], v[188:191], v[120:123]
	v_mfma_f32_16x16x32_bf16 v[108:111], v[156:159], v[196:199], v[108:111]
	v_mfma_f32_16x16x32_bf16 v[104:107], v[164:167], v[196:199], v[104:107]
	v_mfma_f32_16x16x32_bf16 v[92:95], v[156:159], v[204:207], v[92:95]
	v_mfma_f32_16x16x32_bf16 v[88:91], v[164:167], v[204:207], v[88:91]
	v_mfma_f32_16x16x32_bf16 v[76:79], v[156:159], v[212:215], v[76:79]
	v_mfma_f32_16x16x32_bf16 v[72:75], v[164:167], v[212:215], v[72:75]
	s_setprio 0
	s_setprio 1
	v_mfma_f32_16x16x32_bf16 v[116:119], v[168:171], v[184:187], v[116:119]
	v_mfma_f32_16x16x32_bf16 v[112:115], v[176:179], v[184:187], v[112:115]
	v_mfma_f32_16x16x32_bf16 v[100:103], v[168:171], v[192:195], v[100:103]
	v_mfma_f32_16x16x32_bf16 v[96:99], v[176:179], v[192:195], v[96:99]
	v_mfma_f32_16x16x32_bf16 v[84:87], v[168:171], v[200:203], v[84:87]
	v_mfma_f32_16x16x32_bf16 v[80:83], v[176:179], v[200:203], v[80:83]
	v_mfma_f32_16x16x32_bf16 v[68:71], v[168:171], v[208:211], v[68:71]
	v_mfma_f32_16x16x32_bf16 v[64:67], v[176:179], v[208:211], v[64:67]
	v_mfma_f32_16x16x32_bf16 v[116:119], v[172:175], v[188:191], v[116:119]
	v_mfma_f32_16x16x32_bf16 v[112:115], v[180:183], v[188:191], v[112:115]
	v_mfma_f32_16x16x32_bf16 v[100:103], v[172:175], v[196:199], v[100:103]
	v_mfma_f32_16x16x32_bf16 v[96:99], v[180:183], v[196:199], v[96:99]
	v_mfma_f32_16x16x32_bf16 v[84:87], v[172:175], v[204:207], v[84:87]
	v_mfma_f32_16x16x32_bf16 v[80:83], v[180:183], v[204:207], v[80:83]
	v_mfma_f32_16x16x32_bf16 v[68:71], v[172:175], v[212:215], v[68:71]
	v_mfma_f32_16x16x32_bf16 v[64:67], v[180:183], v[212:215], v[64:67]
	s_setprio 0
	s_barrier
; #define PG8_STAGE(bufoff, gbase, voff) do { _Pragma("unroll") for (int _i = 0; _i < 2; ++_i) \
;         __builtin_amdgcn_global_load_lds((const unsigned*)((const char*)(gbase) + (voff)[_i]), (PG8_LAS unsigned*)(lds + (bufoff) + ldsw + _i * 8192), 16, 0, 0); } while (0)
; #define PG8_LDA(dst, b, h) do { _Pragma("unroll") for (int m = 0; m < 4; ++m) _Pragma("unroll") for (int k = 0; k < 2; ++k) dst[m][k] = *(const PG8_LAS bf16x8*)(lds + PG8_SA(b, h) + aoff + m * 2048 + k * 1024); } while (0)
; #define PG8_MMA(ai, bj, At, Bt) do { __builtin_amdgcn_s_setprio(1); _Pragma("unroll") for (int m = 0; m < 4; ++m) _Pragma("unroll") for (int n = 0; n < 2; ++n) _Pragma("unroll") for (int k = 0; k < 2; ++k) \
;         acc[ai][bj][m][n] = __builtin_amdgcn_mfma_f32_16x16x32_bf16(Bt[n][k], At[m][k], acc[ai][bj][m][n], 0, 0, 0); __builtin_amdgcn_s_setprio(0); } while (0)
; #define PG8_WAIT_V(n) asm volatile("s_waitcnt vmcnt(" #n ")" ::: "memory")
; #define PG8_WAIT_L(n) asm volatile("s_waitcnt lgkmcnt(" #n ")" ::: "memory")
; #define PG8_BAR __builtin_amdgcn_s_barrier()
; #define PG8_SCHED __builtin_amdgcn_sched_barrier(0)
; template <class Epi, class Sched, bool ALIGN_EPI = false, bool SP2 = false>
; __device__ __forceinline__ void gemm_phase(PG8_LAS unsigned char* lds, const Gemm g, const Sched& S, const Epi& E) {
;     ...
;             PG8_LDA(At, 1, 1); PG8_STAGE(PG8_SB(1, 0), b3, voffB); PG8_STAGE(PG8_SB(1, 1), b3 + hstep, voffB); PG8_STAGE(PG8_SA(1, 0), a3, voffA);
;             PG8_WAIT_V(8); PG8_WAIT_L(0); PG8_BAR; PG8_MMA(1, 0, At, B0); PG8_MMA(1, 1, At, B1); PG8_BAR; PG8_SCHED;
;     __device__ __forceinline__ void operator()(const f32x4 (&acc)[2][2][4][2], const Unit& u, int wr, int wc, int fr, int fq) const {
;         const int rbase = u.pm * 256 + wr * 64 + fr, cb = u.pn * 256 + wc * 32 + fq * 8;
; #pragma unroll
;         for (int ai = 0; ai < 2; ++ai)
; #pragma unroll
;             for (int m = 0; m < 4; ++m) { const int row = rbase + ai * 128 + m * 16; const f32x4* sp = (const f32x4*)(SSP + (size_t)row * 16);
;                 const f32x4 s4 = (sp[0] + sp[1]) + (sp[2] + sp[3]); const float rstd = __builtin_amdgcn_rsqf(((s4[0] + s4[1]) + (s4[2] + s4[3])) * (1.0f / 1024.0f) + EPS);
	s_add_i32 s36, s66, s39
	v_lshl_add_u64 v[216:217], v[216:217], 0, s[14:15]
	s_mov_b32 m0, s36
	ds_read_b128 v[184:187], v153 offset:49152
	ds_read_b128 v[188:191], v153 offset:50176
	ds_read_b128 v[192:195], v153 offset:51200
	ds_read_b128 v[196:199], v153 offset:52224
	ds_read_b128 v[200:203], v153 offset:53248
	ds_read_b128 v[204:207], v153 offset:54272
	ds_read_b128 v[208:211], v153 offset:55296
	ds_read_b128 v[212:215], v153 offset:56320
	global_load_lds_dwordx4 v[216:217], off
	s_add_i32 m0, s36, 0x2000
	s_add_u32 s34, s34, 0x40080
	v_lshl_add_u64 v[216:217], v[218:219], 0, s[14:15]
	s_addc_u32 s35, s35, 0
	s_add_i32 s36, s67, s39
	global_load_lds_dwordx4 v[216:217], off
	v_lshl_add_u64 v[216:217], s[34:35], 0, v[132:133]
	s_mov_b32 m0, s36
	s_nop 0
	global_load_lds_dwordx4 v[216:217], off
	v_lshl_add_u64 v[216:217], s[34:35], 0, v[128:129]
	s_add_i32 m0, s36, 0x2000
	s_nop 0
	global_load_lds_dwordx4 v[216:217], off
	v_lshl_add_u64 v[216:217], v[220:221], 0, s[14:15]
	s_mov_b32 m0, s49
	s_nop 0
	global_load_lds_dwordx4 v[216:217], off
	v_lshl_add_u64 v[216:217], v[222:223], 0, s[14:15]
	s_mov_b32 m0, s50
	s_nop 0
	global_load_lds_dwordx4 v[216:217], off
	s_waitcnt vmcnt(8)
	s_waitcnt lgkmcnt(0)
	s_barrier
	s_setprio 1
	s_waitcnt lgkmcnt(0)
	v_mfma_f32_16x16x32_bf16 v[60:63], v[144:147], v[184:187], v[60:63]
	v_mfma_f32_16x16x32_bf16 v[56:59], v[160:163], v[184:187], v[56:59]
	v_mfma_f32_16x16x32_bf16 v[44:47], v[144:147], v[192:195], v[44:47]
	v_mfma_f32_16x16x32_bf16 v[40:43], v[160:163], v[192:195], v[40:43]
	v_mfma_f32_16x16x32_bf16 v[28:31], v[144:147], v[200:203], v[28:31]
	v_mfma_f32_16x16x32_bf16 v[24:27], v[160:163], v[200:203], v[24:27]
	v_mfma_f32_16x16x32_bf16 v[12:15], v[144:147], v[208:211], v[12:15]
	v_mfma_f32_16x16x32_bf16 v[8:11], v[160:163], v[208:211], v[8:11]
	v_mfma_f32_16x16x32_bf16 v[60:63], v[156:159], v[188:191], v[60:63]
	v_mfma_f32_16x16x32_bf16 v[56:59], v[164:167], v[188:191], v[56:59]
	v_mfma_f32_16x16x32_bf16 v[44:47], v[156:159], v[196:199], v[44:47]
	v_mfma_f32_16x16x32_bf16 v[40:43], v[164:167], v[196:199], v[40:43]
	v_mfma_f32_16x16x32_bf16 v[28:31], v[156:159], v[204:207], v[28:31]
	v_mfma_f32_16x16x32_bf16 v[24:27], v[164:167], v[204:207], v[24:27]
	v_mfma_f32_16x16x32_bf16 v[12:15], v[156:159], v[212:215], v[12:15]
	v_mfma_f32_16x16x32_bf16 v[8:11], v[164:167], v[212:215], v[8:11]
	s_setprio 0
	s_setprio 1
	v_mfma_f32_16x16x32_bf16 v[52:55], v[168:171], v[184:187], v[52:55]
	v_mfma_f32_16x16x32_bf16 v[48:51], v[176:179], v[184:187], v[48:51]
	v_mfma_f32_16x16x32_bf16 v[36:39], v[168:171], v[192:195], v[36:39]
	v_mfma_f32_16x16x32_bf16 v[32:35], v[176:179], v[192:195], v[32:35]
	v_mfma_f32_16x16x32_bf16 v[20:23], v[168:171], v[200:203], v[20:23]
	v_mfma_f32_16x16x32_bf16 v[16:19], v[176:179], v[200:203], v[16:19]
	v_mfma_f32_16x16x32_bf16 v[4:7], v[168:171], v[208:211], v[4:7]
	v_mfma_f32_16x16x32_bf16 v[0:3], v[176:179], v[208:211], v[0:3]
	v_mfma_f32_16x16x32_bf16 v[52:55], v[172:175], v[188:191], v[52:55]
	v_mfma_f32_16x16x32_bf16 v[48:51], v[180:183], v[188:191], v[48:51]
	v_mfma_f32_16x16x32_bf16 v[36:39], v[172:175], v[196:199], v[36:39]
	v_mfma_f32_16x16x32_bf16 v[32:35], v[180:183], v[196:199], v[32:35]
	v_mfma_f32_16x16x32_bf16 v[20:23], v[172:175], v[204:207], v[20:23]
	v_mfma_f32_16x16x32_bf16 v[16:19], v[180:183], v[204:207], v[16:19]
	v_mfma_f32_16x16x32_bf16 v[4:7], v[172:175], v[212:215], v[4:7]
	v_mfma_f32_16x16x32_bf16 v[0:3], v[180:183], v[212:215], v[0:3]
	s_setprio 0
	s_barrier
	s_mov_b32 s99, 0
	s_add_i32 s65, s65, 2
	s_add_u32 s30, s30, 0x100
	s_addc_u32 s31, s31, 0
	s_add_u32 s63, s63, 0x100
	s_addc_u32 s64, s64, 0
	s_cmp_gt_u32 s65, 13
	s_cbranch_scc0 .LBB0_1540
	v_lshl_add_u32 v146, s28, 8, v148
	v_ashrrev_i32_e32 v147, 31, v146
	v_lshlrev_b64 v[144:145], 6, v[146:147]
	v_lshl_add_u64 v[144:145], s[12:13], 0, v[144:145]
	global_load_dwordx4 v[156:159], v[144:145], off
	global_load_dwordx4 v[160:163], v[144:145], off offset:16
	global_load_dwordx4 v[164:167], v[144:145], off offset:32
	global_load_dwordx4 v[168:171], v[144:145], off offset:48
	global_load_dwordx4 v[172:175], v[144:145], off offset:1024
	global_load_dwordx4 v[176:179], v[144:145], off offset:1040
	global_load_dwordx4 v[180:183], v[144:145], off offset:1056
	global_load_dwordx4 v[184:187], v[144:145], off offset:1072
	global_load_dwordx4 v[188:191], v[144:145], off offset:2048
	global_load_dwordx4 v[192:195], v[144:145], off offset:2064
	global_load_dwordx4 v[196:199], v[144:145], off offset:2080
	global_load_dwordx4 v[200:203], v[144:145], off offset:2096
	global_load_dwordx4 v[204:207], v[144:145], off offset:3072
	global_load_dwordx4 v[208:211], v[144:145], off offset:3088
	global_load_dwordx4 v[212:215], v[144:145], off offset:3104
	global_load_dwordx4 v[216:219], v[144:145], off offset:3120
	s_and_b64 vcc, exec, s[16:17]
	s_cbranch_vccz .LBB0_1543
	s_barrier
; __device__ __forceinline__ u32x4 pack8(const f32x4 a, const f32x4 b) { u32x4 w; w.x = cvt_pk_bf16(a[0], a[1]); w.y = cvt_pk_bf16(a[2], a[3]); w.z = cvt_pk_bf16(b[0], b[1]); w.w = cvt_pk_bf16(b[2], b[3]); return w; }
;     __device__ __forceinline__ void operator()(const f32x4 (&acc)[2][2][4][2], const Unit& u, int wr, int wc, int fr, int fq) const {
;         const int rbase = u.pm * 256 + wr * 64 + fr, cb = u.pn * 256 + wc * 32 + fq * 8;
; #pragma unroll
;         for (int ai = 0; ai < 2; ++ai)
; #pragma unroll
;             for (int m = 0; m < 4; ++m) { const int row = rbase + ai * 128 + m * 16; const f32x4* sp = (const f32x4*)(SSP + (size_t)row * 16);
;                 const f32x4 s4 = (sp[0] + sp[1]) + (sp[2] + sp[3]); const float rstd = __builtin_amdgcn_rsqf(((s4[0] + s4[1]) + (s4[2] + s4[3])) * (1.0f / 1024.0f) + EPS);
; #pragma unroll
;                 for (int bj = 0; bj < 2; ++bj) { f32x4 v0 = acc[ai][bj][m][0] * rstd, v1 = acc[ai][bj][m][1] * rstd;
; #pragma unroll
;                     for (int i = 0; i < 4; ++i) { const float a = fmaxf(v0[i], 0.f), b = fmaxf(v1[i], 0.f); v0[i] = a * a; v1[i] = b * b; }
;                     *(u32x4*)(Z + (size_t)row * FF + cb + bj * 128) = pack8(v0, v1); }
.LBB0_1543:
	v_lshlrev_b64 v[220:221], 13, v[146:147]
	v_lshl_or_b32 v222, s60, 8, v150
	v_ashrrev_i32_e32 v223, 31, v222
	v_lshlrev_b64 v[222:223], 1, v[222:223]
	v_lshl_add_u64 v[220:221], s[8:9], 0, v[220:221]
	v_lshl_add_u64 v[220:221], v[220:221], 0, v[222:223]
	v_mov_b64_e32 v[224:225], v[220:221]
	s_mov_b64 s[98:99], 0x2000
	s_mov_b64 s[100:101], 0xa0000
	v_lshl_add_u64 v[222:223], v[144:145], 0, s[98:99]
	s_mov_b64 s[98:99], 0x20000
	s_waitcnt vmcnt(12)
	v_pk_add_f32 v[156:157], v[156:157], v[160:161]
	v_pk_add_f32 v[158:159], v[158:159], v[162:163]
	v_pk_add_f32 v[164:165], v[164:165], v[168:169]
	v_pk_add_f32 v[166:167], v[166:167], v[170:171]
	v_pk_add_f32 v[156:157], v[156:157], v[164:165]
	v_pk_add_f32 v[158:159], v[158:159], v[166:167]
	v_add_f32_e32 v156, v156, v157
	v_add_f32_e32 v158, v158, v159
	v_add_f32_e32 v156, v156, v158
	v_fmamk_f32 v156, v156, 0x3a800000, v154
	v_rsq_f32_e32 v144, v156
	s_waitcnt vmcnt(8)
	v_pk_add_f32 v[172:173], v[172:173], v[176:177]
	v_pk_add_f32 v[174:175], v[174:175], v[178:179]
	v_pk_add_f32 v[180:181], v[180:181], v[184:185]
	v_pk_add_f32 v[182:183], v[182:183], v[186:187]
	v_pk_add_f32 v[172:173], v[172:173], v[180:181]
	v_pk_add_f32 v[174:175], v[174:175], v[182:183]
	v_add_f32_e32 v172, v172, v173
	v_add_f32_e32 v174, v174, v175
	v_add_f32_e32 v172, v172, v174
	v_fmamk_f32 v172, v172, 0x3a800000, v154
	v_rsq_f32_e32 v145, v172
	s_waitcnt vmcnt(4)
	v_pk_add_f32 v[188:189], v[188:189], v[192:193]
	v_pk_add_f32 v[190:191], v[190:191], v[194:195]
	v_pk_add_f32 v[196:197], v[196:197], v[200:201]
	v_pk_add_f32 v[198:199], v[198:199], v[202:203]
	v_pk_add_f32 v[188:189], v[188:189], v[196:197]
	v_pk_add_f32 v[190:191], v[190:191], v[198:199]
	v_add_f32_e32 v188, v188, v189
	v_add_f32_e32 v190, v190, v191
	v_add_f32_e32 v188, v188, v190
	v_fmamk_f32 v188, v188, 0x3a800000, v154
	v_rsq_f32_e32 v146, v188
	s_waitcnt vmcnt(0)
	v_pk_add_f32 v[204:205], v[204:205], v[208:209]
	v_pk_add_f32 v[206:207], v[206:207], v[210:211]
	v_pk_add_f32 v[212:213], v[212:213], v[216:217]
	v_pk_add_f32 v[214:215], v[214:215], v[218:219]
	v_pk_add_f32 v[204:205], v[204:205], v[212:213]
	v_pk_add_f32 v[206:207], v[206:207], v[214:215]
	v_add_f32_e32 v204, v204, v205
	v_add_f32_e32 v206, v206, v207
	v_add_f32_e32 v204, v204, v206
	v_fmamk_f32 v204, v204, 0x3a800000, v154
	v_rsq_f32_e32 v147, v204
	global_load_dwordx4 v[156:159], v[222:223], off
	global_load_dwordx4 v[160:163], v[222:223], off offset:16
	global_load_dwordx4 v[164:167], v[222:223], off offset:32
	global_load_dwordx4 v[168:171], v[222:223], off offset:48
	global_load_dwordx4 v[172:175], v[222:223], off offset:1024
	global_load_dwordx4 v[176:179], v[222:223], off offset:1040
	global_load_dwordx4 v[180:183], v[222:223], off offset:1056
	global_load_dwordx4 v[184:187], v[222:223], off offset:1072
	global_load_dwordx4 v[188:191], v[222:223], off offset:2048
	global_load_dwordx4 v[192:195], v[222:223], off offset:2064
	global_load_dwordx4 v[196:199], v[222:223], off offset:2080
	global_load_dwordx4 v[200:203], v[222:223], off offset:2096
	global_load_dwordx4 v[204:207], v[222:223], off offset:3072
	global_load_dwordx4 v[208:211], v[222:223], off offset:3088
	global_load_dwordx4 v[212:215], v[222:223], off offset:3104
	global_load_dwordx4 v[216:219], v[222:223], off offset:3120
	v_mul_f32_e32 v112, v144, v112
	v_mul_f32_e32 v113, v144, v113
	v_mul_f32_e32 v114, v144, v114
	v_mul_f32_e32 v115, v144, v115
	v_mul_f32_e32 v116, v144, v116
	v_mul_f32_e32 v117, v144, v117
	v_mul_f32_e32 v118, v144, v118
	v_mul_f32_e32 v119, v144, v119
	v_mul_f32_e32 v120, v144, v120
	v_mul_f32_e32 v121, v144, v121
	v_mul_f32_e32 v122, v144, v122
	v_mul_f32_e32 v123, v144, v123
	v_mul_f32_e32 v124, v144, v124
	v_mul_f32_e32 v125, v144, v125
	v_mul_f32_e32 v126, v144, v126
	v_mul_f32_e32 v127, v144, v127
	v_max_f32_e32 v112, 0, v112
	v_max_f32_e32 v113, 0, v113
	v_max_f32_e32 v114, 0, v114
	v_max_f32_e32 v115, 0, v115
	v_max_f32_e32 v116, 0, v116
	v_max_f32_e32 v117, 0, v117
	v_max_f32_e32 v118, 0, v118
	v_max_f32_e32 v119, 0, v119
	v_max_f32_e32 v120, 0, v120
	v_max_f32_e32 v121, 0, v121
	v_max_f32_e32 v122, 0, v122
	v_max_f32_e32 v123, 0, v123
	v_max_f32_e32 v124, 0, v124
	v_max_f32_e32 v125, 0, v125
	v_max_f32_e32 v126, 0, v126
	v_max_f32_e32 v127, 0, v127
	v_mul_f32_e32 v112, v112, v112
	v_mul_f32_e32 v113, v113, v113
	v_mul_f32_e32 v114, v114, v114
	v_mul_f32_e32 v115, v115, v115
	v_mul_f32_e32 v116, v116, v116
	v_mul_f32_e32 v117, v117, v117
	v_mul_f32_e32 v118, v118, v118
	v_mul_f32_e32 v119, v119, v119
	v_mul_f32_e32 v120, v120, v120
	v_mul_f32_e32 v121, v121, v121
	v_mul_f32_e32 v122, v122, v122
	v_mul_f32_e32 v123, v123, v123
	v_mul_f32_e32 v124, v124, v124
	v_mul_f32_e32 v125, v125, v125
	v_mul_f32_e32 v126, v126, v126
	v_mul_f32_e32 v127, v127, v127
	v_cvt_pk_bf16_f32 v124, v124, v125
	v_cvt_pk_bf16_f32 v125, v126, v127
	v_cvt_pk_bf16_f32 v126, v120, v121
	v_cvt_pk_bf16_f32 v127, v122, v123
	v_cvt_pk_bf16_f32 v116, v116, v117
	v_cvt_pk_bf16_f32 v117, v118, v119
	v_cvt_pk_bf16_f32 v118, v112, v113
	v_cvt_pk_bf16_f32 v119, v114, v115
	global_store_dwordx4 v[220:221], v[124:127], off
	global_store_dwordx4 v[220:221], v[116:119], off offset:256
	v_lshl_add_u64 v[220:221], v[220:221], 0, s[98:99]
	v_mul_f32_e32 v96, v145, v96
	v_mul_f32_e32 v97, v145, v97
	v_mul_f32_e32 v98, v145, v98
	v_mul_f32_e32 v99, v145, v99
	v_mul_f32_e32 v100, v145, v100
	v_mul_f32_e32 v101, v145, v101
	v_mul_f32_e32 v102, v145, v102
	v_mul_f32_e32 v103, v145, v103
	v_mul_f32_e32 v104, v145, v104
	v_mul_f32_e32 v105, v145, v105
	v_mul_f32_e32 v106, v145, v106
	v_mul_f32_e32 v107, v145, v107
; __device__ __forceinline__ u32x4 pack8(const f32x4 a, const f32x4 b) { u32x4 w; w.x = cvt_pk_bf16(a[0], a[1]); w.y = cvt_pk_bf16(a[2], a[3]); w.z = cvt_pk_bf16(b[0], b[1]); w.w = cvt_pk_bf16(b[2], b[3]); return w; }
;     __device__ __forceinline__ void operator()(const f32x4 (&acc)[2][2][4][2], const Unit& u, int wr, int wc, int fr, int fq) const {
;     ...
;             for (int m = 0; m < 4; ++m) { const int row = rbase + ai * 128 + m * 16; const f32x4* sp = (const f32x4*)(SSP + (size_t)row * 16);
;                 const f32x4 s4 = (sp[0] + sp[1]) + (sp[2] + sp[3]); const float rstd = __builtin_amdgcn_rsqf(((s4[0] + s4[1]) + (s4[2] + s4[3])) * (1.0f / 1024.0f) + EPS);
; #pragma unroll
;                 for (int bj = 0; bj < 2; ++bj) { f32x4 v0 = acc[ai][bj][m][0] * rstd, v1 = acc[ai][bj][m][1] * rstd;
; #pragma unroll
;                     for (int i = 0; i < 4; ++i) { const float a = fmaxf(v0[i], 0.f), b = fmaxf(v1[i], 0.f); v0[i] = a * a; v1[i] = b * b; }
;                     *(u32x4*)(Z + (size_t)row * FF + cb + bj * 128) = pack8(v0, v1); }
	v_mul_f32_e32 v108, v145, v108
	v_mul_f32_e32 v109, v145, v109
	v_mul_f32_e32 v110, v145, v110
	v_mul_f32_e32 v111, v145, v111
	v_max_f32_e32 v96, 0, v96
	v_max_f32_e32 v97, 0, v97
	v_max_f32_e32 v98, 0, v98
	v_max_f32_e32 v99, 0, v99
	v_max_f32_e32 v100, 0, v100
	v_max_f32_e32 v101, 0, v101
	v_max_f32_e32 v102, 0, v102
	v_max_f32_e32 v103, 0, v103
	v_max_f32_e32 v104, 0, v104
	v_max_f32_e32 v105, 0, v105
	v_max_f32_e32 v106, 0, v106
	v_max_f32_e32 v107, 0, v107
	v_max_f32_e32 v108, 0, v108
	v_max_f32_e32 v109, 0, v109
	v_max_f32_e32 v110, 0, v110
	v_max_f32_e32 v111, 0, v111
	v_mul_f32_e32 v96, v96, v96
	v_mul_f32_e32 v97, v97, v97
	v_mul_f32_e32 v98, v98, v98
	v_mul_f32_e32 v99, v99, v99
	v_mul_f32_e32 v100, v100, v100
	v_mul_f32_e32 v101, v101, v101
	v_mul_f32_e32 v102, v102, v102
	v_mul_f32_e32 v103, v103, v103
	v_mul_f32_e32 v104, v104, v104
	v_mul_f32_e32 v105, v105, v105
	v_mul_f32_e32 v106, v106, v106
	v_mul_f32_e32 v107, v107, v107
	v_mul_f32_e32 v108, v108, v108
	v_mul_f32_e32 v109, v109, v109
	v_mul_f32_e32 v110, v110, v110
	v_mul_f32_e32 v111, v111, v111
	v_cvt_pk_bf16_f32 v108, v108, v109
	v_cvt_pk_bf16_f32 v109, v110, v111
	v_cvt_pk_bf16_f32 v110, v104, v105
	v_cvt_pk_bf16_f32 v111, v106, v107
	v_cvt_pk_bf16_f32 v100, v100, v101
	v_cvt_pk_bf16_f32 v101, v102, v103
	v_cvt_pk_bf16_f32 v102, v96, v97
	v_cvt_pk_bf16_f32 v103, v98, v99
	global_store_dwordx4 v[220:221], v[108:111], off
	global_store_dwordx4 v[220:221], v[100:103], off offset:256
	v_lshl_add_u64 v[220:221], v[220:221], 0, s[98:99]
	v_mul_f32_e32 v80, v146, v80
	v_mul_f32_e32 v81, v146, v81
	v_mul_f32_e32 v82, v146, v82
	v_mul_f32_e32 v83, v146, v83
	v_mul_f32_e32 v84, v146, v84
	v_mul_f32_e32 v85, v146, v85
	v_mul_f32_e32 v86, v146, v86
	v_mul_f32_e32 v87, v146, v87
	v_mul_f32_e32 v88, v146, v88
	v_mul_f32_e32 v89, v146, v89
	v_mul_f32_e32 v90, v146, v90
	v_mul_f32_e32 v91, v146, v91
	v_mul_f32_e32 v92, v146, v92
	v_mul_f32_e32 v93, v146, v93
	v_mul_f32_e32 v94, v146, v94
	v_mul_f32_e32 v95, v146, v95
	v_max_f32_e32 v80, 0, v80
	v_max_f32_e32 v81, 0, v81
	v_max_f32_e32 v82, 0, v82
	v_max_f32_e32 v83, 0, v83
	v_max_f32_e32 v84, 0, v84
	v_max_f32_e32 v85, 0, v85
	v_max_f32_e32 v86, 0, v86
	v_max_f32_e32 v87, 0, v87
	v_max_f32_e32 v88, 0, v88
	v_max_f32_e32 v89, 0, v89
	v_max_f32_e32 v90, 0, v90
	v_max_f32_e32 v91, 0, v91
	v_max_f32_e32 v92, 0, v92
	v_max_f32_e32 v93, 0, v93
	v_max_f32_e32 v94, 0, v94
	v_max_f32_e32 v95, 0, v95
	v_mul_f32_e32 v80, v80, v80
	v_mul_f32_e32 v81, v81, v81
	v_mul_f32_e32 v82, v82, v82
	v_mul_f32_e32 v83, v83, v83
	v_mul_f32_e32 v84, v84, v84
	v_mul_f32_e32 v85, v85, v85
	v_mul_f32_e32 v86, v86, v86
	v_mul_f32_e32 v87, v87, v87
	v_mul_f32_e32 v88, v88, v88
	v_mul_f32_e32 v89, v89, v89
	v_mul_f32_e32 v90, v90, v90
	v_mul_f32_e32 v91, v91, v91
	v_mul_f32_e32 v92, v92, v92
	v_mul_f32_e32 v93, v93, v93
	v_mul_f32_e32 v94, v94, v94
	v_mul_f32_e32 v95, v95, v95
	v_cvt_pk_bf16_f32 v92, v92, v93
	v_cvt_pk_bf16_f32 v93, v94, v95
	v_cvt_pk_bf16_f32 v94, v88, v89
	v_cvt_pk_bf16_f32 v95, v90, v91
	v_cvt_pk_bf16_f32 v84, v84, v85
	v_cvt_pk_bf16_f32 v85, v86, v87
	v_cvt_pk_bf16_f32 v86, v80, v81
	v_cvt_pk_bf16_f32 v87, v82, v83
	global_store_dwordx4 v[220:221], v[92:95], off
	global_store_dwordx4 v[220:221], v[84:87], off offset:256
	v_lshl_add_u64 v[220:221], v[220:221], 0, s[98:99]
	v_mul_f32_e32 v64, v147, v64
	v_mul_f32_e32 v65, v147, v65
	v_mul_f32_e32 v66, v147, v66
	v_mul_f32_e32 v67, v147, v67
	v_mul_f32_e32 v68, v147, v68
	v_mul_f32_e32 v69, v147, v69
	v_mul_f32_e32 v70, v147, v70
	v_mul_f32_e32 v71, v147, v71
	v_mul_f32_e32 v72, v147, v72
	v_mul_f32_e32 v73, v147, v73
	v_mul_f32_e32 v74, v147, v74
	v_mul_f32_e32 v75, v147, v75
	v_mul_f32_e32 v76, v147, v76
	v_mul_f32_e32 v77, v147, v77
	v_mul_f32_e32 v78, v147, v78
	v_mul_f32_e32 v79, v147, v79
	v_max_f32_e32 v64, 0, v64
	v_max_f32_e32 v65, 0, v65
	v_max_f32_e32 v66, 0, v66
	v_max_f32_e32 v67, 0, v67
	v_max_f32_e32 v68, 0, v68
	v_max_f32_e32 v69, 0, v69
	v_max_f32_e32 v70, 0, v70
	v_max_f32_e32 v71, 0, v71
	v_max_f32_e32 v72, 0, v72
	v_max_f32_e32 v73, 0, v73
	v_max_f32_e32 v74, 0, v74
	v_max_f32_e32 v75, 0, v75
	v_max_f32_e32 v76, 0, v76
	v_max_f32_e32 v77, 0, v77
	v_max_f32_e32 v78, 0, v78
	v_max_f32_e32 v79, 0, v79
	v_mul_f32_e32 v64, v64, v64
	v_mul_f32_e32 v65, v65, v65
	v_mul_f32_e32 v66, v66, v66
	v_mul_f32_e32 v67, v67, v67
	v_mul_f32_e32 v68, v68, v68
	v_mul_f32_e32 v69, v69, v69
	v_mul_f32_e32 v70, v70, v70
	v_mul_f32_e32 v71, v71, v71
	v_mul_f32_e32 v72, v72, v72
	v_mul_f32_e32 v73, v73, v73
	v_mul_f32_e32 v74, v74, v74
	v_mul_f32_e32 v75, v75, v75
	v_mul_f32_e32 v76, v76, v76
	v_mul_f32_e32 v77, v77, v77
	v_mul_f32_e32 v78, v78, v78
	v_mul_f32_e32 v79, v79, v79
	v_cvt_pk_bf16_f32 v76, v76, v77
	v_cvt_pk_bf16_f32 v77, v78, v79
	v_cvt_pk_bf16_f32 v78, v72, v73
	v_cvt_pk_bf16_f32 v79, v74, v75
	v_cvt_pk_bf16_f32 v68, v68, v69
	v_cvt_pk_bf16_f32 v69, v70, v71
	v_cvt_pk_bf16_f32 v70, v64, v65
	v_cvt_pk_bf16_f32 v71, v66, v67
	global_store_dwordx4 v[220:221], v[76:79], off
	global_store_dwordx4 v[220:221], v[68:71], off offset:256
	v_lshl_add_u64 v[220:221], v[220:221], 0, s[100:101]
	s_waitcnt vmcnt(20)
	v_pk_add_f32 v[156:157], v[156:157], v[160:161]
	v_pk_add_f32 v[158:159], v[158:159], v[162:163]
	v_pk_add_f32 v[164:165], v[164:165], v[168:169]
	v_pk_add_f32 v[166:167], v[166:167], v[170:171]
	v_pk_add_f32 v[156:157], v[156:157], v[164:165]
	v_pk_add_f32 v[158:159], v[158:159], v[166:167]
	v_add_f32_e32 v156, v156, v157
	v_add_f32_e32 v158, v158, v159
	v_add_f32_e32 v156, v156, v158
	v_fmamk_f32 v156, v156, 0x3a800000, v154
	v_rsq_f32_e32 v144, v156
	s_waitcnt vmcnt(16)
; __device__ __forceinline__ u32x4 pack8(const f32x4 a, const f32x4 b) { u32x4 w; w.x = cvt_pk_bf16(a[0], a[1]); w.y = cvt_pk_bf16(a[2], a[3]); w.z = cvt_pk_bf16(b[0], b[1]); w.w = cvt_pk_bf16(b[2], b[3]); return w; }
;     __device__ __forceinline__ void operator()(const f32x4 (&acc)[2][2][4][2], const Unit& u, int wr, int wc, int fr, int fq) const {
;     ...
;             for (int m = 0; m < 4; ++m) { const int row = rbase + ai * 128 + m * 16; const f32x4* sp = (const f32x4*)(SSP + (size_t)row * 16);
;                 const f32x4 s4 = (sp[0] + sp[1]) + (sp[2] + sp[3]); const float rstd = __builtin_amdgcn_rsqf(((s4[0] + s4[1]) + (s4[2] + s4[3])) * (1.0f / 1024.0f) + EPS);
; #pragma unroll
;                 for (int bj = 0; bj < 2; ++bj) { f32x4 v0 = acc[ai][bj][m][0] * rstd, v1 = acc[ai][bj][m][1] * rstd;
; #pragma unroll
;                     for (int i = 0; i < 4; ++i) { const float a = fmaxf(v0[i], 0.f), b = fmaxf(v1[i], 0.f); v0[i] = a * a; v1[i] = b * b; }
;                     *(u32x4*)(Z + (size_t)row * FF + cb + bj * 128) = pack8(v0, v1); }
	v_pk_add_f32 v[172:173], v[172:173], v[176:177]
	v_pk_add_f32 v[174:175], v[174:175], v[178:179]
	v_pk_add_f32 v[180:181], v[180:181], v[184:185]
	v_pk_add_f32 v[182:183], v[182:183], v[186:187]
	v_pk_add_f32 v[172:173], v[172:173], v[180:181]
	v_pk_add_f32 v[174:175], v[174:175], v[182:183]
	v_add_f32_e32 v172, v172, v173
	v_add_f32_e32 v174, v174, v175
	v_add_f32_e32 v172, v172, v174
	v_fmamk_f32 v172, v172, 0x3a800000, v154
	v_rsq_f32_e32 v145, v172
	s_waitcnt vmcnt(12)
	v_pk_add_f32 v[188:189], v[188:189], v[192:193]
	v_pk_add_f32 v[190:191], v[190:191], v[194:195]
	v_pk_add_f32 v[196:197], v[196:197], v[200:201]
	v_pk_add_f32 v[198:199], v[198:199], v[202:203]
	v_pk_add_f32 v[188:189], v[188:189], v[196:197]
	v_pk_add_f32 v[190:191], v[190:191], v[198:199]
	v_add_f32_e32 v188, v188, v189
	v_add_f32_e32 v190, v190, v191
	v_add_f32_e32 v188, v188, v190
	v_fmamk_f32 v188, v188, 0x3a800000, v154
	v_rsq_f32_e32 v146, v188
	s_waitcnt vmcnt(8)
	v_pk_add_f32 v[204:205], v[204:205], v[208:209]
	v_pk_add_f32 v[206:207], v[206:207], v[210:211]
	v_pk_add_f32 v[212:213], v[212:213], v[216:217]
	v_pk_add_f32 v[214:215], v[214:215], v[218:219]
	v_pk_add_f32 v[204:205], v[204:205], v[212:213]
	v_pk_add_f32 v[206:207], v[206:207], v[214:215]
	v_add_f32_e32 v204, v204, v205
	v_add_f32_e32 v206, v206, v207
	v_add_f32_e32 v204, v204, v206
	v_fmamk_f32 v204, v204, 0x3a800000, v154
	v_rsq_f32_e32 v147, v204
	v_mul_f32_e32 v48, v144, v48
	v_mul_f32_e32 v49, v144, v49
	v_mul_f32_e32 v50, v144, v50
	v_mul_f32_e32 v51, v144, v51
	v_mul_f32_e32 v52, v144, v52
	v_mul_f32_e32 v53, v144, v53
	v_mul_f32_e32 v54, v144, v54
	v_mul_f32_e32 v55, v144, v55
	v_mul_f32_e32 v56, v144, v56
	v_mul_f32_e32 v57, v144, v57
	v_mul_f32_e32 v58, v144, v58
	v_mul_f32_e32 v59, v144, v59
	v_mul_f32_e32 v60, v144, v60
	v_mul_f32_e32 v61, v144, v61
	v_mul_f32_e32 v62, v144, v62
	v_mul_f32_e32 v63, v144, v63
	v_max_f32_e32 v48, 0, v48
	v_max_f32_e32 v49, 0, v49
	v_max_f32_e32 v50, 0, v50
	v_max_f32_e32 v51, 0, v51
	v_max_f32_e32 v52, 0, v52
	v_max_f32_e32 v53, 0, v53
	v_max_f32_e32 v54, 0, v54
	v_max_f32_e32 v55, 0, v55
	v_max_f32_e32 v56, 0, v56
	v_max_f32_e32 v57, 0, v57
	v_max_f32_e32 v58, 0, v58
	v_max_f32_e32 v59, 0, v59
	v_max_f32_e32 v60, 0, v60
	v_max_f32_e32 v61, 0, v61
	v_max_f32_e32 v62, 0, v62
	v_max_f32_e32 v63, 0, v63
	v_mul_f32_e32 v48, v48, v48
	v_mul_f32_e32 v49, v49, v49
	v_mul_f32_e32 v50, v50, v50
	v_mul_f32_e32 v51, v51, v51
	v_mul_f32_e32 v52, v52, v52
	v_mul_f32_e32 v53, v53, v53
	v_mul_f32_e32 v54, v54, v54
	v_mul_f32_e32 v55, v55, v55
	v_mul_f32_e32 v56, v56, v56
	v_mul_f32_e32 v57, v57, v57
	v_mul_f32_e32 v58, v58, v58
	v_mul_f32_e32 v59, v59, v59
	v_mul_f32_e32 v60, v60, v60
	v_mul_f32_e32 v61, v61, v61
	v_mul_f32_e32 v62, v62, v62
	v_mul_f32_e32 v63, v63, v63
	v_cvt_pk_bf16_f32 v60, v60, v61
	v_cvt_pk_bf16_f32 v61, v62, v63
	v_cvt_pk_bf16_f32 v62, v56, v57
	v_cvt_pk_bf16_f32 v63, v58, v59
	v_cvt_pk_bf16_f32 v52, v52, v53
	v_cvt_pk_bf16_f32 v53, v54, v55
	v_cvt_pk_bf16_f32 v54, v48, v49
	v_cvt_pk_bf16_f32 v55, v50, v51
	global_store_dwordx4 v[220:221], v[60:63], off
	global_store_dwordx4 v[220:221], v[52:55], off offset:256
	v_lshl_add_u64 v[220:221], v[220:221], 0, s[98:99]
	v_mul_f32_e32 v32, v145, v32
	v_mul_f32_e32 v33, v145, v33
	v_mul_f32_e32 v34, v145, v34
	v_mul_f32_e32 v35, v145, v35
	v_mul_f32_e32 v36, v145, v36
	v_mul_f32_e32 v37, v145, v37
	v_mul_f32_e32 v38, v145, v38
	v_mul_f32_e32 v39, v145, v39
	v_mul_f32_e32 v40, v145, v40
	v_mul_f32_e32 v41, v145, v41
	v_mul_f32_e32 v42, v145, v42
	v_mul_f32_e32 v43, v145, v43
	v_mul_f32_e32 v44, v145, v44
	v_mul_f32_e32 v45, v145, v45
	v_mul_f32_e32 v46, v145, v46
	v_mul_f32_e32 v47, v145, v47
	v_max_f32_e32 v32, 0, v32
	v_max_f32_e32 v33, 0, v33
	v_max_f32_e32 v34, 0, v34
	v_max_f32_e32 v35, 0, v35
	v_max_f32_e32 v36, 0, v36
	v_max_f32_e32 v37, 0, v37
	v_max_f32_e32 v38, 0, v38
	v_max_f32_e32 v39, 0, v39
	v_max_f32_e32 v40, 0, v40
	v_max_f32_e32 v41, 0, v41
	v_max_f32_e32 v42, 0, v42
	v_max_f32_e32 v43, 0, v43
	v_max_f32_e32 v44, 0, v44
	v_max_f32_e32 v45, 0, v45
	v_max_f32_e32 v46, 0, v46
	v_max_f32_e32 v47, 0, v47
	v_mul_f32_e32 v32, v32, v32
	v_mul_f32_e32 v33, v33, v33
	v_mul_f32_e32 v34, v34, v34
	v_mul_f32_e32 v35, v35, v35
	v_mul_f32_e32 v36, v36, v36
	v_mul_f32_e32 v37, v37, v37
	v_mul_f32_e32 v38, v38, v38
; #define PG8_BAR __builtin_amdgcn_s_barrier()
; __device__ __forceinline__ u32x4 pack8(const f32x4 a, const f32x4 b) { u32x4 w; w.x = cvt_pk_bf16(a[0], a[1]); w.y = cvt_pk_bf16(a[2], a[3]); w.z = cvt_pk_bf16(b[0], b[1]); w.w = cvt_pk_bf16(b[2], b[3]); return w; }
; template <class Epi, class Sched, bool ALIGN_EPI = false, bool SP2 = false>
; __device__ __forceinline__ void gemm_phase(PG8_LAS unsigned char* lds, const Gemm g, const Sched& S, const Epi& E) {
;     ...
;         if constexpr (ALIGN_EPI) { if (wr == 0) PG8_BAR; }
;         if constexpr (!Epi::AFTER_DRAIN) { E(acc, cur, wr, wc, fr, fq); S.done(cur); }
;         if (!has_next) break;
;     __device__ __forceinline__ void operator()(const f32x4 (&acc)[2][2][4][2], const Unit& u, int wr, int wc, int fr, int fq) const {
;     ...
;                 for (int bj = 0; bj < 2; ++bj) { f32x4 v0 = acc[ai][bj][m][0] * rstd, v1 = acc[ai][bj][m][1] * rstd;
; #pragma unroll
;                     for (int i = 0; i < 4; ++i) { const float a = fmaxf(v0[i], 0.f), b = fmaxf(v1[i], 0.f); v0[i] = a * a; v1[i] = b * b; }
;                     *(u32x4*)(Z + (size_t)row * FF + cb + bj * 128) = pack8(v0, v1); }
	v_mul_f32_e32 v39, v39, v39
	v_mul_f32_e32 v40, v40, v40
	v_mul_f32_e32 v41, v41, v41
	v_mul_f32_e32 v42, v42, v42
	v_mul_f32_e32 v43, v43, v43
	v_mul_f32_e32 v44, v44, v44
	v_mul_f32_e32 v45, v45, v45
	v_mul_f32_e32 v46, v46, v46
	v_mul_f32_e32 v47, v47, v47
	v_cvt_pk_bf16_f32 v44, v44, v45
	v_cvt_pk_bf16_f32 v45, v46, v47
	v_cvt_pk_bf16_f32 v46, v40, v41
	v_cvt_pk_bf16_f32 v47, v42, v43
	v_cvt_pk_bf16_f32 v36, v36, v37
	v_cvt_pk_bf16_f32 v37, v38, v39
	v_cvt_pk_bf16_f32 v38, v32, v33
	v_cvt_pk_bf16_f32 v39, v34, v35
	global_store_dwordx4 v[220:221], v[44:47], off
	global_store_dwordx4 v[220:221], v[36:39], off offset:256
	v_lshl_add_u64 v[220:221], v[220:221], 0, s[98:99]
	v_mul_f32_e32 v16, v146, v16
	v_mul_f32_e32 v17, v146, v17
	v_mul_f32_e32 v18, v146, v18
	v_mul_f32_e32 v19, v146, v19
	v_mul_f32_e32 v20, v146, v20
	v_mul_f32_e32 v21, v146, v21
	v_mul_f32_e32 v22, v146, v22
	v_mul_f32_e32 v23, v146, v23
	v_mul_f32_e32 v24, v146, v24
	v_mul_f32_e32 v25, v146, v25
	v_mul_f32_e32 v26, v146, v26
	v_mul_f32_e32 v27, v146, v27
	v_mul_f32_e32 v28, v146, v28
	v_mul_f32_e32 v29, v146, v29
	v_mul_f32_e32 v30, v146, v30
	v_mul_f32_e32 v31, v146, v31
	v_max_f32_e32 v16, 0, v16
	v_max_f32_e32 v17, 0, v17
	v_max_f32_e32 v18, 0, v18
	v_max_f32_e32 v19, 0, v19
	v_max_f32_e32 v20, 0, v20
	v_max_f32_e32 v21, 0, v21
	v_max_f32_e32 v22, 0, v22
	v_max_f32_e32 v23, 0, v23
	v_max_f32_e32 v24, 0, v24
	v_max_f32_e32 v25, 0, v25
	v_max_f32_e32 v26, 0, v26
	v_max_f32_e32 v27, 0, v27
	v_max_f32_e32 v28, 0, v28
	v_max_f32_e32 v29, 0, v29
	v_max_f32_e32 v30, 0, v30
	v_max_f32_e32 v31, 0, v31
	v_mul_f32_e32 v16, v16, v16
	v_mul_f32_e32 v17, v17, v17
	v_mul_f32_e32 v18, v18, v18
	v_mul_f32_e32 v19, v19, v19
	v_mul_f32_e32 v20, v20, v20
	v_mul_f32_e32 v21, v21, v21
	v_mul_f32_e32 v22, v22, v22
	v_mul_f32_e32 v23, v23, v23
	v_mul_f32_e32 v24, v24, v24
	v_mul_f32_e32 v25, v25, v25
	v_mul_f32_e32 v26, v26, v26
	v_mul_f32_e32 v27, v27, v27
	v_mul_f32_e32 v28, v28, v28
	v_mul_f32_e32 v29, v29, v29
	v_mul_f32_e32 v30, v30, v30
	v_mul_f32_e32 v31, v31, v31
	v_cvt_pk_bf16_f32 v28, v28, v29
	v_cvt_pk_bf16_f32 v29, v30, v31
	v_cvt_pk_bf16_f32 v30, v24, v25
	v_cvt_pk_bf16_f32 v31, v26, v27
	v_cvt_pk_bf16_f32 v20, v20, v21
	v_cvt_pk_bf16_f32 v21, v22, v23
	v_cvt_pk_bf16_f32 v22, v16, v17
	v_cvt_pk_bf16_f32 v23, v18, v19
	global_store_dwordx4 v[220:221], v[28:31], off
	global_store_dwordx4 v[220:221], v[20:23], off offset:256
	v_lshl_add_u64 v[220:221], v[220:221], 0, s[98:99]
	v_mul_f32_e32 v0, v147, v0
	v_mul_f32_e32 v1, v147, v1
	v_mul_f32_e32 v2, v147, v2
	v_mul_f32_e32 v3, v147, v3
	v_mul_f32_e32 v4, v147, v4
	v_mul_f32_e32 v5, v147, v5
	v_mul_f32_e32 v6, v147, v6
	v_mul_f32_e32 v7, v147, v7
	v_mul_f32_e32 v8, v147, v8
	v_mul_f32_e32 v9, v147, v9
	v_mul_f32_e32 v10, v147, v10
	v_mul_f32_e32 v11, v147, v11
	v_mul_f32_e32 v12, v147, v12
	v_mul_f32_e32 v13, v147, v13
	v_mul_f32_e32 v14, v147, v14
	v_mul_f32_e32 v15, v147, v15
	v_max_f32_e32 v0, 0, v0
	v_max_f32_e32 v1, 0, v1
	v_max_f32_e32 v2, 0, v2
	v_max_f32_e32 v3, 0, v3
	v_max_f32_e32 v4, 0, v4
	v_max_f32_e32 v5, 0, v5
	v_max_f32_e32 v6, 0, v6
	v_max_f32_e32 v7, 0, v7
	v_max_f32_e32 v8, 0, v8
	v_max_f32_e32 v9, 0, v9
	v_max_f32_e32 v10, 0, v10
	v_max_f32_e32 v11, 0, v11
	v_max_f32_e32 v12, 0, v12
	v_max_f32_e32 v13, 0, v13
	v_max_f32_e32 v14, 0, v14
	v_max_f32_e32 v15, 0, v15
	v_mul_f32_e32 v0, v0, v0
	v_mul_f32_e32 v1, v1, v1
	v_mul_f32_e32 v2, v2, v2
	v_mul_f32_e32 v3, v3, v3
	v_mul_f32_e32 v4, v4, v4
	v_mul_f32_e32 v5, v5, v5
	v_mul_f32_e32 v6, v6, v6
	v_mul_f32_e32 v7, v7, v7
	v_mul_f32_e32 v8, v8, v8
	v_mul_f32_e32 v9, v9, v9
	v_mul_f32_e32 v10, v10, v10
	v_mul_f32_e32 v11, v11, v11
	v_mul_f32_e32 v12, v12, v12
	v_mul_f32_e32 v13, v13, v13
	v_mul_f32_e32 v14, v14, v14
	v_mul_f32_e32 v15, v15, v15
	v_cvt_pk_bf16_f32 v12, v12, v13
	v_cvt_pk_bf16_f32 v13, v14, v15
	v_cvt_pk_bf16_f32 v14, v8, v9
	v_cvt_pk_bf16_f32 v15, v10, v11
	v_cvt_pk_bf16_f32 v4, v4, v5
	v_cvt_pk_bf16_f32 v5, v6, v7
	v_cvt_pk_bf16_f32 v6, v0, v1
	v_cvt_pk_bf16_f32 v7, v2, v3
	global_store_dwordx4 v[220:221], v[12:15], off
	global_store_dwordx4 v[220:221], v[4:7], off offset:256
	s_andn2_b64 vcc, exec, s[4:5]
	s_mov_b64 s[4:5], -1
	s_cbranch_vccnz .LBB0_1536
	s_andn2_b64 vcc, exec, s[6:7]
	s_cbranch_vccnz .LBB0_1535
	s_barrier
	s_branch .LBB0_1535

; #define PG8_STAGE(bufoff, gbase, voff) do { _Pragma("unroll") for (int _i = 0; _i < 2; ++_i) \
;         __builtin_amdgcn_global_load_lds((const unsigned*)((const char*)(gbase) + (voff)[_i]), (PG8_LAS unsigned*)(lds + (bufoff) + ldsw + _i * 8192), 16, 0, 0); } while (0)
; #define PG8_LDA(dst, b, h) do { _Pragma("unroll") for (int m = 0; m < 4; ++m) _Pragma("unroll") for (int k = 0; k < 2; ++k) dst[m][k] = *(const PG8_LAS bf16x8*)(lds + PG8_SA(b, h) + aoff + m * 2048 + k * 1024); } while (0)
; #define PG8_LDB(dst, b, h) do { _Pragma("unroll") for (int n = 0; n < 2; ++n) _Pragma("unroll") for (int k = 0; k < 2; ++k) dst[n][k] = *(const PG8_LAS bf16x8*)(lds + PG8_SB(b, h) + boff + n * 2048 + k * 1024); } while (0)
; #define PG8_MMA(ai, bj, At, Bt) do { __builtin_amdgcn_s_setprio(1); _Pragma("unroll") for (int m = 0; m < 4; ++m) _Pragma("unroll") for (int n = 0; n < 2; ++n) _Pragma("unroll") for (int k = 0; k < 2; ++k) \
;         acc[ai][bj][m][n] = __builtin_amdgcn_mfma_f32_16x16x32_bf16(Bt[n][k], At[m][k], acc[ai][bj][m][n], 0, 0, 0); __builtin_amdgcn_s_setprio(0); } while (0)
; #define PG8_WAIT_V(n) asm volatile("s_waitcnt vmcnt(" #n ")" ::: "memory")
; #define PG8_WAIT_L(n) asm volatile("s_waitcnt lgkmcnt(" #n ")" ::: "memory")
; #define PG8_BAR __builtin_amdgcn_s_barrier()
; #define PG8_SCHED __builtin_amdgcn_sched_barrier(0)
; template <class Epi, class Sched, bool ALIGN_EPI = false, bool SP2 = false>
; __device__ __forceinline__ void gemm_phase(PG8_LAS unsigned char* lds, const Gemm g, const Sched& S, const Epi& E) {
;     ...
;             PG8_WAIT_V(8); PG8_WAIT_L(0); PG8_BAR; PG8_MMA(1, 0, At, B0); PG8_MMA(1, 1, At, B1); PG8_BAR; PG8_SCHED;
;             PG8_LDB(B0, 1, 0); PG8_LDB(B1, 1, 1); PG8_SCHED; PG8_LDA(At, 1, 0); PG8_STAGE(PG8_SA(0, 1), a2 + hstep, voffA);
;             PG8_WAIT_V(8); PG8_WAIT_L(0); PG8_BAR; PG8_MMA(0, 0, At, B0); PG8_MMA(0, 1, At, B1); PG8_BAR; PG8_SCHED;
.Lrj_P6_1:
	s_waitcnt lgkmcnt(0)
	s_barrier
	s_setprio 1
	s_waitcnt lgkmcnt(0)
	v_mfma_f32_16x16x32_bf16 v[60:63], v[152:155], v[184:187], v[60:63]
	v_mfma_f32_16x16x32_bf16 v[56:59], v[160:163], v[184:187], v[56:59]
	v_mfma_f32_16x16x32_bf16 v[44:47], v[152:155], v[192:195], v[44:47]
	v_mfma_f32_16x16x32_bf16 v[40:43], v[160:163], v[192:195], v[40:43]
	v_mfma_f32_16x16x32_bf16 v[28:31], v[152:155], v[200:203], v[28:31]
	v_mfma_f32_16x16x32_bf16 v[24:27], v[160:163], v[200:203], v[24:27]
	v_mfma_f32_16x16x32_bf16 v[12:15], v[152:155], v[208:211], v[12:15]
	v_mfma_f32_16x16x32_bf16 v[8:11], v[160:163], v[208:211], v[8:11]
	v_mfma_f32_16x16x32_bf16 v[60:63], v[156:159], v[188:191], v[60:63]
	v_mfma_f32_16x16x32_bf16 v[56:59], v[164:167], v[188:191], v[56:59]
	v_mfma_f32_16x16x32_bf16 v[44:47], v[156:159], v[196:199], v[44:47]
	v_mfma_f32_16x16x32_bf16 v[40:43], v[164:167], v[196:199], v[40:43]
	v_mfma_f32_16x16x32_bf16 v[28:31], v[156:159], v[204:207], v[28:31]
	v_mfma_f32_16x16x32_bf16 v[24:27], v[164:167], v[204:207], v[24:27]
	v_mfma_f32_16x16x32_bf16 v[12:15], v[156:159], v[212:215], v[12:15]
	v_mfma_f32_16x16x32_bf16 v[8:11], v[164:167], v[212:215], v[8:11]
	s_setprio 0
	s_setprio 1
	v_mfma_f32_16x16x32_bf16 v[52:55], v[168:171], v[184:187], v[52:55]
	v_mfma_f32_16x16x32_bf16 v[48:51], v[176:179], v[184:187], v[48:51]
	v_mfma_f32_16x16x32_bf16 v[36:39], v[168:171], v[192:195], v[36:39]
	v_mfma_f32_16x16x32_bf16 v[32:35], v[176:179], v[192:195], v[32:35]
	v_mfma_f32_16x16x32_bf16 v[20:23], v[168:171], v[200:203], v[20:23]
	v_mfma_f32_16x16x32_bf16 v[16:19], v[176:179], v[200:203], v[16:19]
	v_mfma_f32_16x16x32_bf16 v[4:7], v[168:171], v[208:211], v[4:7]
	v_mfma_f32_16x16x32_bf16 v[0:3], v[176:179], v[208:211], v[0:3]
	v_mfma_f32_16x16x32_bf16 v[52:55], v[172:175], v[188:191], v[52:55]
	v_mfma_f32_16x16x32_bf16 v[48:51], v[180:183], v[188:191], v[48:51]
	v_mfma_f32_16x16x32_bf16 v[36:39], v[172:175], v[196:199], v[36:39]
	v_mfma_f32_16x16x32_bf16 v[32:35], v[180:183], v[196:199], v[32:35]
	v_mfma_f32_16x16x32_bf16 v[20:23], v[172:175], v[204:207], v[20:23]
	v_mfma_f32_16x16x32_bf16 v[16:19], v[180:183], v[204:207], v[16:19]
	v_mfma_f32_16x16x32_bf16 v[4:7], v[172:175], v[212:215], v[4:7]
	v_mfma_f32_16x16x32_bf16 v[0:3], v[180:183], v[212:215], v[0:3]
	s_setprio 0
	s_barrier
	s_add_i32 s69, 0, 0x18000
	s_add_i32 s70, 0, 0x1c000
	v_add_u32_e32 v164, s69, v147
	v_add_u32_e32 v180, s70, v147
	ds_read_b128 v[152:155], v164
	ds_read_b128 v[156:159], v164 offset:1024
	ds_read_b128 v[160:163], v164 offset:2048
	ds_read_b128 v[164:167], v164 offset:3072
	ds_read_b128 v[168:171], v180
	ds_read_b128 v[172:175], v180 offset:1024
	ds_read_b128 v[176:179], v180 offset:2048
	ds_read_b128 v[180:183], v180 offset:3072
	s_add_u32 s34, s34, 0x100000
	s_addc_u32 s35, s35, 0
	s_mov_b32 m0, s43
	v_lshl_add_u64 v[222:223], s[34:35], 0, v[134:135]
	ds_read_b128 v[184:187], v151 offset:32768
	ds_read_b128 v[188:191], v151 offset:33792
	ds_read_b128 v[192:195], v151 offset:34816
	ds_read_b128 v[196:199], v151 offset:35840
	ds_read_b128 v[200:203], v151 offset:36864
	ds_read_b128 v[204:207], v151 offset:37888
	ds_read_b128 v[208:211], v151 offset:38912
	ds_read_b128 v[212:215], v151 offset:39936
	global_load_lds_dwordx4 v[222:223], off
	v_lshl_add_u64 v[222:223], s[34:35], 0, v[130:131]
	s_mov_b32 m0, s46
	s_nop 0
	global_load_lds_dwordx4 v[222:223], off
	s_waitcnt vmcnt(8)
	s_waitcnt lgkmcnt(0)
	s_barrier
	s_setprio 1
	s_waitcnt lgkmcnt(0)
	v_mfma_f32_16x16x32_bf16 v[124:127], v[152:155], v[184:187], v[124:127]
	v_mfma_f32_16x16x32_bf16 v[120:123], v[160:163], v[184:187], v[120:123]
	v_mfma_f32_16x16x32_bf16 v[108:111], v[152:155], v[192:195], v[108:111]
	v_mfma_f32_16x16x32_bf16 v[104:107], v[160:163], v[192:195], v[104:107]
	v_mfma_f32_16x16x32_bf16 v[92:95], v[152:155], v[200:203], v[92:95]
	v_mfma_f32_16x16x32_bf16 v[88:91], v[160:163], v[200:203], v[88:91]
	v_mfma_f32_16x16x32_bf16 v[76:79], v[152:155], v[208:211], v[76:79]
	v_mfma_f32_16x16x32_bf16 v[72:75], v[160:163], v[208:211], v[72:75]
	v_mfma_f32_16x16x32_bf16 v[124:127], v[156:159], v[188:191], v[124:127]
	v_mfma_f32_16x16x32_bf16 v[120:123], v[164:167], v[188:191], v[120:123]
	v_mfma_f32_16x16x32_bf16 v[108:111], v[156:159], v[196:199], v[108:111]
	v_mfma_f32_16x16x32_bf16 v[104:107], v[164:167], v[196:199], v[104:107]
	v_mfma_f32_16x16x32_bf16 v[92:95], v[156:159], v[204:207], v[92:95]
	v_mfma_f32_16x16x32_bf16 v[88:91], v[164:167], v[204:207], v[88:91]
	v_mfma_f32_16x16x32_bf16 v[76:79], v[156:159], v[212:215], v[76:79]
	v_mfma_f32_16x16x32_bf16 v[72:75], v[164:167], v[212:215], v[72:75]
	s_setprio 0
	s_setprio 1
	v_mfma_f32_16x16x32_bf16 v[116:119], v[168:171], v[184:187], v[116:119]
	v_mfma_f32_16x16x32_bf16 v[112:115], v[176:179], v[184:187], v[112:115]
	v_mfma_f32_16x16x32_bf16 v[100:103], v[168:171], v[192:195], v[100:103]
	v_mfma_f32_16x16x32_bf16 v[96:99], v[176:179], v[192:195], v[96:99]
	v_mfma_f32_16x16x32_bf16 v[84:87], v[168:171], v[200:203], v[84:87]
	v_mfma_f32_16x16x32_bf16 v[80:83], v[176:179], v[200:203], v[80:83]
	v_mfma_f32_16x16x32_bf16 v[68:71], v[168:171], v[208:211], v[68:71]
	v_mfma_f32_16x16x32_bf16 v[64:67], v[176:179], v[208:211], v[64:67]
	v_mfma_f32_16x16x32_bf16 v[116:119], v[172:175], v[188:191], v[116:119]
	v_mfma_f32_16x16x32_bf16 v[112:115], v[180:183], v[188:191], v[112:115]
	v_mfma_f32_16x16x32_bf16 v[100:103], v[172:175], v[196:199], v[100:103]
	v_mfma_f32_16x16x32_bf16 v[96:99], v[180:183], v[196:199], v[96:99]
	v_mfma_f32_16x16x32_bf16 v[84:87], v[172:175], v[204:207], v[84:87]
	v_mfma_f32_16x16x32_bf16 v[80:83], v[180:183], v[204:207], v[80:83]
	v_mfma_f32_16x16x32_bf16 v[68:71], v[172:175], v[212:215], v[68:71]
	v_mfma_f32_16x16x32_bf16 v[64:67], v[180:183], v[212:215], v[64:67]
	s_setprio 0
	s_barrier
; #define PG8_STAGE(bufoff, gbase, voff) do { _Pragma("unroll") for (int _i = 0; _i < 2; ++_i) \
;         __builtin_amdgcn_global_load_lds((const unsigned*)((const char*)(gbase) + (voff)[_i]), (PG8_LAS unsigned*)(lds + (bufoff) + ldsw + _i * 8192), 16, 0, 0); } while (0)
; #define PG8_LDA(dst, b, h) do { _Pragma("unroll") for (int m = 0; m < 4; ++m) _Pragma("unroll") for (int k = 0; k < 2; ++k) dst[m][k] = *(const PG8_LAS bf16x8*)(lds + PG8_SA(b, h) + aoff + m * 2048 + k * 1024); } while (0)
; #define PG8_MMA(ai, bj, At, Bt) do { __builtin_amdgcn_s_setprio(1); _Pragma("unroll") for (int m = 0; m < 4; ++m) _Pragma("unroll") for (int n = 0; n < 2; ++n) _Pragma("unroll") for (int k = 0; k < 2; ++k) \
;         acc[ai][bj][m][n] = __builtin_amdgcn_mfma_f32_16x16x32_bf16(Bt[n][k], At[m][k], acc[ai][bj][m][n], 0, 0, 0); __builtin_amdgcn_s_setprio(0); } while (0)
; #define PG8_WAIT_V(n) asm volatile("s_waitcnt vmcnt(" #n ")" ::: "memory")
; #define PG8_WAIT_L(n) asm volatile("s_waitcnt lgkmcnt(" #n ")" ::: "memory")
; #define PG8_BAR __builtin_amdgcn_s_barrier()
; #define PG8_SCHED __builtin_amdgcn_sched_barrier(0)
; template <class Epi, class Sched, bool ALIGN_EPI = false, bool SP2 = false>
; __device__ __forceinline__ void gemm_phase(PG8_LAS unsigned char* lds, const Gemm g, const Sched& S, const Epi& E) {
;     ...
;             PG8_LDA(At, 1, 1); PG8_STAGE(PG8_SB(1, 0), b3, voffB); PG8_STAGE(PG8_SB(1, 1), b3 + hstep, voffB); PG8_STAGE(PG8_SA(1, 0), a3, voffA);
;             PG8_WAIT_V(8); PG8_WAIT_L(0); PG8_BAR; PG8_MMA(1, 0, At, B0); PG8_MMA(1, 1, At, B1); PG8_BAR; PG8_SCHED;
;     __device__ __forceinline__ void operator()(const f32x4 (&acc)[2][2][4][2], const Unit& u, int wr, int wc, int fr, int fq) const {
;         const int rbase = u.pm * 256 + wr * 64 + fr, cb = u.pn * 256 + wc * 32 + fq * 8;
; #pragma unroll
;         for (int ai = 0; ai < 2; ++ai)
; #pragma unroll
;             for (int m = 0; m < 4; ++m) { float* yr = y + (size_t)(rbase + ai * 128 + m * 16) * 1024 + cb;
; #pragma unroll
;                 for (int bj = 0; bj < 2; ++bj) { float* yp = yr + bj * 128; const f32x4 a = *(const f32x4*)yp + acc[ai][bj][m][0], b = *(const f32x4*)(yp + 4) + acc[ai][bj][m][1]; *(f32x4*)yp = a; *(f32x4*)(yp + 4) = b; }
	s_add_i32 s34, s69, s39
	v_lshl_add_u64 v[144:145], v[144:145], 0, s[6:7]
	s_mov_b32 m0, s34
	ds_read_b128 v[184:187], v151 offset:49152
	ds_read_b128 v[188:191], v151 offset:50176
	ds_read_b128 v[192:195], v151 offset:51200
	ds_read_b128 v[196:199], v151 offset:52224
	ds_read_b128 v[200:203], v151 offset:53248
	ds_read_b128 v[204:207], v151 offset:54272
	ds_read_b128 v[208:211], v151 offset:55296
	ds_read_b128 v[212:215], v151 offset:56320
	global_load_lds_dwordx4 v[144:145], off
	s_add_i32 m0, s34, 0x2000
	s_add_u32 s30, s30, 0x100080
	v_lshl_add_u64 v[144:145], v[216:217], 0, s[6:7]
	s_addc_u32 s31, s31, 0
	s_add_i32 s34, s70, s39
	global_load_lds_dwordx4 v[144:145], off
	v_lshl_add_u64 v[144:145], s[30:31], 0, v[132:133]
	s_mov_b32 m0, s34
	s_nop 0
	global_load_lds_dwordx4 v[144:145], off
	v_lshl_add_u64 v[144:145], s[30:31], 0, v[128:129]
	s_add_i32 m0, s34, 0x2000
	s_nop 0
	global_load_lds_dwordx4 v[144:145], off
	v_lshl_add_u64 v[144:145], v[218:219], 0, s[6:7]
	s_mov_b32 m0, s48
	s_nop 0
	global_load_lds_dwordx4 v[144:145], off
	v_lshl_add_u64 v[144:145], v[220:221], 0, s[6:7]
	s_mov_b32 m0, s49
	s_nop 0
	global_load_lds_dwordx4 v[144:145], off
	s_waitcnt vmcnt(8)
	s_waitcnt lgkmcnt(0)
	s_barrier
	s_setprio 1
	s_waitcnt lgkmcnt(0)
	v_mfma_f32_16x16x32_bf16 v[60:63], v[152:155], v[184:187], v[60:63]
	v_mfma_f32_16x16x32_bf16 v[56:59], v[160:163], v[184:187], v[56:59]
	v_mfma_f32_16x16x32_bf16 v[44:47], v[152:155], v[192:195], v[44:47]
	v_mfma_f32_16x16x32_bf16 v[40:43], v[160:163], v[192:195], v[40:43]
	v_mfma_f32_16x16x32_bf16 v[28:31], v[152:155], v[200:203], v[28:31]
	v_mfma_f32_16x16x32_bf16 v[24:27], v[160:163], v[200:203], v[24:27]
	v_mfma_f32_16x16x32_bf16 v[12:15], v[152:155], v[208:211], v[12:15]
	v_mfma_f32_16x16x32_bf16 v[8:11], v[160:163], v[208:211], v[8:11]
	v_mfma_f32_16x16x32_bf16 v[60:63], v[156:159], v[188:191], v[60:63]
	v_mfma_f32_16x16x32_bf16 v[56:59], v[164:167], v[188:191], v[56:59]
	v_mfma_f32_16x16x32_bf16 v[44:47], v[156:159], v[196:199], v[44:47]
	v_mfma_f32_16x16x32_bf16 v[40:43], v[164:167], v[196:199], v[40:43]
	v_mfma_f32_16x16x32_bf16 v[28:31], v[156:159], v[204:207], v[28:31]
	v_mfma_f32_16x16x32_bf16 v[24:27], v[164:167], v[204:207], v[24:27]
	v_mfma_f32_16x16x32_bf16 v[12:15], v[156:159], v[212:215], v[12:15]
	v_mfma_f32_16x16x32_bf16 v[8:11], v[164:167], v[212:215], v[8:11]
	s_setprio 0
	s_setprio 1
	v_mfma_f32_16x16x32_bf16 v[52:55], v[168:171], v[184:187], v[52:55]
	v_mfma_f32_16x16x32_bf16 v[48:51], v[176:179], v[184:187], v[48:51]
	v_mfma_f32_16x16x32_bf16 v[36:39], v[168:171], v[192:195], v[36:39]
	v_mfma_f32_16x16x32_bf16 v[32:35], v[176:179], v[192:195], v[32:35]
	v_mfma_f32_16x16x32_bf16 v[20:23], v[168:171], v[200:203], v[20:23]
	v_mfma_f32_16x16x32_bf16 v[16:19], v[176:179], v[200:203], v[16:19]
	v_mfma_f32_16x16x32_bf16 v[4:7], v[168:171], v[208:211], v[4:7]
	v_mfma_f32_16x16x32_bf16 v[0:3], v[176:179], v[208:211], v[0:3]
	v_mfma_f32_16x16x32_bf16 v[52:55], v[172:175], v[188:191], v[52:55]
	v_mfma_f32_16x16x32_bf16 v[48:51], v[180:183], v[188:191], v[48:51]
	v_mfma_f32_16x16x32_bf16 v[36:39], v[172:175], v[196:199], v[36:39]
	v_mfma_f32_16x16x32_bf16 v[32:35], v[180:183], v[196:199], v[32:35]
	v_mfma_f32_16x16x32_bf16 v[20:23], v[172:175], v[204:207], v[20:23]
	v_mfma_f32_16x16x32_bf16 v[16:19], v[180:183], v[204:207], v[16:19]
	v_mfma_f32_16x16x32_bf16 v[4:7], v[172:175], v[212:215], v[4:7]
	v_mfma_f32_16x16x32_bf16 v[0:3], v[180:183], v[212:215], v[0:3]
	s_setprio 0
	s_barrier
	s_mov_b32 s99, 0
	s_add_i32 s68, s68, 2
	s_add_u32 s28, s28, 0x100
	s_addc_u32 s29, s29, 0
	s_add_u32 s66, s66, 0x100
	s_addc_u32 s67, s67, 0
	s_cmp_gt_u32 s68, 61
	s_cbranch_scc0 .LBB0_2136
	v_and_b32_e32 v216, 0xfffffff7, v146
	v_lshl_add_u32 v216, s26, 8, v216
	v_bfe_u32 v220, v146, 3, 1
	v_lshl_add_u32 v220, v220, 2, v148
	v_lshl_or_b32 v220, s63, 8, v220
	v_ashrrev_i32_e32 v217, 31, v216
	v_ashrrev_i32_e32 v221, 31, v220
	v_lshlrev_b64 v[216:217], 12, v[216:217]
	v_lshlrev_b64 v[220:221], 2, v[220:221]
	v_lshl_add_u64 v[216:217], s[84:85], 0, v[216:217]
	v_lshl_add_u64 v[216:217], v[216:217], 0, v[220:221]
	s_mov_b64 s[98:99], 0x8000
	v_lshl_add_u64 v[218:219], v[216:217], 0, s[98:99]
	v_mov_b64_e32 v[220:221], v[216:217]
	v_mov_b64_e32 v[222:223], v[218:219]
	s_mov_b64 s[98:99], 0x10000
	s_mov_b64 s[100:101], 0x50000
	global_load_dwordx4 v[152:155], v[216:217], off
	global_load_dwordx4 v[156:159], v[218:219], off
	global_load_dwordx4 v[160:163], v[216:217], off offset:512
	global_load_dwordx4 v[164:167], v[218:219], off offset:512
	v_lshl_add_u64 v[216:217], v[216:217], 0, s[98:99]
	v_lshl_add_u64 v[218:219], v[218:219], 0, s[98:99]
	global_load_dwordx4 v[168:171], v[216:217], off
	global_load_dwordx4 v[172:175], v[218:219], off
	global_load_dwordx4 v[176:179], v[216:217], off offset:512
	global_load_dwordx4 v[180:183], v[218:219], off offset:512
	v_lshl_add_u64 v[216:217], v[216:217], 0, s[98:99]
	v_lshl_add_u64 v[218:219], v[218:219], 0, s[98:99]
	global_load_dwordx4 v[184:187], v[216:217], off
	global_load_dwordx4 v[188:191], v[218:219], off
	global_load_dwordx4 v[192:195], v[216:217], off offset:512
	global_load_dwordx4 v[196:199], v[218:219], off offset:512
	v_lshl_add_u64 v[216:217], v[216:217], 0, s[98:99]
	v_lshl_add_u64 v[218:219], v[218:219], 0, s[98:99]
	global_load_dwordx4 v[200:203], v[216:217], off
	global_load_dwordx4 v[204:207], v[218:219], off
	global_load_dwordx4 v[208:211], v[216:217], off offset:512
	global_load_dwordx4 v[212:215], v[218:219], off offset:512
	v_lshl_add_u64 v[216:217], v[216:217], 0, s[100:101]
	v_lshl_add_u64 v[218:219], v[218:219], 0, s[100:101]
	global_load_dwordx4 v[228:231], v[216:217], off
	global_load_dwordx4 v[232:235], v[218:219], off
	global_load_dwordx4 v[236:239], v[216:217], off offset:512
	global_load_dwordx4 v[240:243], v[218:219], off offset:512
	v_lshl_add_u64 v[216:217], v[216:217], 0, s[98:99]
	v_lshl_add_u64 v[218:219], v[218:219], 0, s[98:99]
	s_and_b64 vcc, exec, s[8:9]
	s_cbranch_vccz .LBB0_2139
	s_barrier
